# hyena PROMPT unit: the 16 half-wave dwordx2 gate loads also widened to 8 dwordx4 + v_permlane32_swap (loads and stores of the epilogue now 16 B per lane)
# baseline (speedup 1.0000x reference)
.LBB0_504:
	s_or_b64 exec, exec, s[4:5]
	v_sub_u32_e32 v2, 0, v10
	v_bfe_u32 v136, v10, 5, 1
	v_and_b32_e32 v0, 31, v10
	s_ashr_i32 s4, s1, 4
	v_and_b32_e32 v2, 3, v2
	s_and_b32 s1, s4, -4
	v_lshlrev_b32_e32 v139, 4, v136
	v_add_lshl_u32 v0, v2, v0, 1
	s_sub_i32 s7, s1, 31
	v_mul_u32_u24_e32 v3, 0x4440, v2
	s_add_i32 s2, 0, 0x11400
	v_sub_u32_e32 v2, v139, v0
	v_add3_u32 v2, s2, v3, v2
	s_lshl_b32 s2, s7, 8
	v_subrev_u32_e32 v2, s2, v2
	v_add_u32_e32 v4, 0x2140, v2
	s_waitcnt lgkmcnt(0)
	s_barrier
	v_add_u32_e32 v5, 0x2160, v2
	ds_read2_b64 v[108:111], v4 offset1:1
	ds_read2_b64 v[96:99], v5 offset1:1
	v_add_u32_e32 v4, 0x2180, v2
	v_add_u32_e32 v5, 0x21a0, v2
	ds_read2_b64 v[104:107], v4 offset1:1
	ds_read2_b64 v[92:95], v5 offset1:1
	v_add_u32_e32 v4, 0x21c0, v2
	v_add_u32_e32 v5, 0x21e0, v2
	ds_read2_b64 v[100:103], v4 offset1:1
	ds_read2_b64 v[84:87], v5 offset1:1
	v_add_u32_e32 v4, 0x2200, v2
	v_add_u32_e32 v5, 0x2220, v2
	ds_read2_b64 v[116:119], v4 offset1:1
	ds_read2_b64 v[112:115], v5 offset1:1
	v_add_u32_e32 v4, 0x2240, v2
	v_add_u32_e32 v5, 0x2260, v2
	ds_read2_b64 v[88:91], v4 offset1:1
	ds_read2_b64 v[76:79], v5 offset1:1
	v_add_u32_e32 v4, 0x2280, v2
	v_add_u32_e32 v5, 0x22a0, v2
	ds_read2_b64 v[80:83], v4 offset1:1
	ds_read2_b64 v[68:71], v5 offset1:1
	v_add_u32_e32 v4, 0x22c0, v2
	v_add_u32_e32 v2, 0x22e0, v2
	ds_read2_b64 v[72:75], v4 offset1:1
	ds_read2_b64 v[64:67], v2 offset1:1
	s_or_b32 s2, s4, 3
	s_lshl_b32 s4, s4, 8
	v_and_b32_e32 v137, 3, v10
	v_bfe_u32 v138, v10, 2, 3
	v_sub_u32_e32 v0, v3, v0
	s_and_b32 s4, s4, 0xfffffc00
	v_mul_u32_u24_e32 v1, 0x2240, v138
	s_add_i32 s5, 0, 0x11200
	v_mul_u32_u24_e32 v2, 0x110, v137
	v_subrev_u32_e32 v0, s4, v0
	v_mov_b32_e32 v48, 0
	v_add_u32_e32 v140, s5, v139
	v_add3_u32 v141, v1, v2, 0
	v_add_u32_e32 v142, 29, v137
	v_add_u32_e32 v143, 0, v0
	v_mov_b32_e32 v49, v48
	v_mov_b32_e32 v50, v48
	v_mov_b32_e32 v51, v48
	v_mov_b32_e32 v52, v48
	v_mov_b32_e32 v53, v48
	v_mov_b32_e32 v54, v48
	v_mov_b32_e32 v55, v48
	v_mov_b32_e32 v56, v48
	v_mov_b32_e32 v57, v48
	v_mov_b32_e32 v58, v48
	v_mov_b32_e32 v59, v48
	v_mov_b32_e32 v60, v48
	v_mov_b32_e32 v61, v48
	v_mov_b32_e32 v62, v48
	v_mov_b32_e32 v63, v48
	v_mov_b32_e32 v32, v48
	v_mov_b32_e32 v33, v48
	v_mov_b32_e32 v34, v48
	v_mov_b32_e32 v35, v48
	v_mov_b32_e32 v36, v48
	v_mov_b32_e32 v37, v48
	v_mov_b32_e32 v38, v48
	v_mov_b32_e32 v39, v48
	v_mov_b32_e32 v40, v48
	v_mov_b32_e32 v41, v48
	v_mov_b32_e32 v42, v48
	v_mov_b32_e32 v43, v48
	v_mov_b32_e32 v44, v48
	v_mov_b32_e32 v45, v48
	v_mov_b32_e32 v46, v48
	v_mov_b32_e32 v47, v48
	v_mov_b32_e32 v16, v48
	v_mov_b32_e32 v17, v48
	v_mov_b32_e32 v18, v48
	v_mov_b32_e32 v19, v48
	v_mov_b32_e32 v20, v48
	v_mov_b32_e32 v21, v48
	v_mov_b32_e32 v22, v48
	v_mov_b32_e32 v23, v48
	v_mov_b32_e32 v24, v48
	v_mov_b32_e32 v25, v48
	v_mov_b32_e32 v26, v48
	v_mov_b32_e32 v27, v48
	v_mov_b32_e32 v28, v48
	v_mov_b32_e32 v29, v48
	v_mov_b32_e32 v30, v48
	v_mov_b32_e32 v31, v48
	v_mov_b32_e32 v0, v48
	v_mov_b32_e32 v1, v48
	v_mov_b32_e32 v2, v48
	v_mov_b32_e32 v3, v48
	v_mov_b32_e32 v4, v48
	v_mov_b32_e32 v5, v48
	v_mov_b32_e32 v6, v48
	v_mov_b32_e32 v7, v48
	v_mov_b32_e32 v8, v48
	v_mov_b32_e32 v9, v48
	v_mov_b32_e32 v10, v48
	v_mov_b32_e32 v11, v48
	v_mov_b32_e32 v12, v48
	v_mov_b32_e32 v13, v48
	v_mov_b32_e32 v14, v48
	v_mov_b32_e32 v15, v48
	v_or_b32_e32 v222, s1, v137
	v_lshlrev_b32_e32 v223, 12, v138
	v_lshl_add_u32 v222, v222, 7, v223
	v_ashrrev_i32_e32 v223, 31, v222
	v_lshl_add_u64 v[222:223], v[222:223], 0, s[40:41]
	v_lshl_or_b32 v222, v136, 3, v222
	v_lshlrev_b64 v[222:223], 1, v[222:223]
	v_lshl_add_u64 v[222:223], s[22:23], 0, v[222:223]
	global_load_dwordx4 v[186:189], v[222:223], off
	global_load_dwordx4 v[190:193], v[222:223], off offset:32
	global_load_dwordx4 v[194:197], v[222:223], off offset:64
	global_load_dwordx4 v[198:201], v[222:223], off offset:96
	global_load_dwordx4 v[202:205], v[222:223], off offset:128
	global_load_dwordx4 v[206:209], v[222:223], off offset:160
	global_load_dwordx4 v[210:213], v[222:223], off offset:192
	global_load_dwordx4 v[232:235], v[222:223], off offset:224
	s_cmpk_lt_u32 s1, 16
	s_cbranch_scc1 .Lpb_a
	s_barrier

.Lpb_b:
	v_or_b32_e32 v64, s1, v137
	v_lshlrev_b32_e32 v65, 12, v138
	v_lshl_add_u32 v64, v64, 7, v65
	v_ashrrev_i32_e32 v65, 31, v64
	v_lshl_add_u64 v[64:65], v[64:65], 0, s[40:41]
	v_lshl_or_b32 v64, v136, 3, v64
	v_lshlrev_b64 v[66:67], 1, v[64:65]
	v_lshl_add_u64 v[64:65], s[24:25], 0, v[66:67]
	s_mov_b64 s[4:5], 0
	s_waitcnt vmcnt(0)
	v_permlane32_swap_b32 v186, v188
	v_permlane32_swap_b32 v187, v189
	v_permlane32_swap_b32 v190, v192
	v_permlane32_swap_b32 v191, v193
	v_permlane32_swap_b32 v194, v196
	v_permlane32_swap_b32 v195, v197
	v_permlane32_swap_b32 v198, v200
	v_permlane32_swap_b32 v199, v201
	v_permlane32_swap_b32 v202, v204
	v_permlane32_swap_b32 v203, v205
	v_permlane32_swap_b32 v206, v208
	v_permlane32_swap_b32 v207, v209
	v_permlane32_swap_b32 v210, v212
	v_permlane32_swap_b32 v211, v213
	v_permlane32_swap_b32 v232, v234
	v_permlane32_swap_b32 v233, v235
	v_lshlrev_b32_e32 v224, 16, v186
	v_and_b32_e32 v225, 0xffff0000, v186
	v_lshlrev_b32_e32 v226, 16, v187
	v_and_b32_e32 v227, 0xffff0000, v187
	v_pk_mul_f32 v[48:49], v[48:49], v[224:225]
	v_pk_mul_f32 v[50:51], v[50:51], v[226:227]
	v_cvt_pk_bf16_f32 v48, v48, v49
	v_cvt_pk_bf16_f32 v49, v50, v51
	v_lshlrev_b32_e32 v228, 16, v188
	v_and_b32_e32 v229, 0xffff0000, v188
	v_lshlrev_b32_e32 v230, 16, v189
	v_and_b32_e32 v231, 0xffff0000, v189
	v_pk_mul_f32 v[52:53], v[52:53], v[228:229]
	v_pk_mul_f32 v[54:55], v[54:55], v[230:231]
	v_cvt_pk_bf16_f32 v50, v52, v53
	v_cvt_pk_bf16_f32 v51, v54, v55
	s_nop 1
	v_permlane32_swap_b32 v48, v50
	v_permlane32_swap_b32 v49, v51
	global_store_dwordx4 v[64:65], v[48:51], off
	v_lshlrev_b32_e32 v224, 16, v190
	v_and_b32_e32 v225, 0xffff0000, v190
	v_lshlrev_b32_e32 v226, 16, v191
	v_and_b32_e32 v227, 0xffff0000, v191
	v_pk_mul_f32 v[56:57], v[56:57], v[224:225]
	v_pk_mul_f32 v[58:59], v[58:59], v[226:227]
	v_cvt_pk_bf16_f32 v56, v56, v57
	v_cvt_pk_bf16_f32 v57, v58, v59
	v_lshlrev_b32_e32 v228, 16, v192
	v_and_b32_e32 v229, 0xffff0000, v192
	v_lshlrev_b32_e32 v230, 16, v193
	v_and_b32_e32 v231, 0xffff0000, v193
	v_pk_mul_f32 v[60:61], v[60:61], v[228:229]
	v_pk_mul_f32 v[62:63], v[62:63], v[230:231]
	v_cvt_pk_bf16_f32 v58, v60, v61
	v_cvt_pk_bf16_f32 v59, v62, v63
	s_nop 1
	v_permlane32_swap_b32 v56, v58
	v_permlane32_swap_b32 v57, v59
	global_store_dwordx4 v[64:65], v[56:59], off offset:32
	v_lshlrev_b32_e32 v224, 16, v194
	v_and_b32_e32 v225, 0xffff0000, v194
	v_lshlrev_b32_e32 v226, 16, v195
	v_and_b32_e32 v227, 0xffff0000, v195
	v_pk_mul_f32 v[32:33], v[32:33], v[224:225]
	v_pk_mul_f32 v[34:35], v[34:35], v[226:227]
	v_cvt_pk_bf16_f32 v32, v32, v33
	v_cvt_pk_bf16_f32 v33, v34, v35
	v_lshlrev_b32_e32 v228, 16, v196
	v_and_b32_e32 v229, 0xffff0000, v196
	v_lshlrev_b32_e32 v230, 16, v197
	v_and_b32_e32 v231, 0xffff0000, v197
	v_pk_mul_f32 v[36:37], v[36:37], v[228:229]
	v_pk_mul_f32 v[38:39], v[38:39], v[230:231]
	v_cvt_pk_bf16_f32 v34, v36, v37
	v_cvt_pk_bf16_f32 v35, v38, v39
	s_nop 1
	v_permlane32_swap_b32 v32, v34
	v_permlane32_swap_b32 v33, v35
	global_store_dwordx4 v[64:65], v[32:35], off offset:64
	v_lshlrev_b32_e32 v224, 16, v198
	v_and_b32_e32 v225, 0xffff0000, v198
	v_lshlrev_b32_e32 v226, 16, v199
	v_and_b32_e32 v227, 0xffff0000, v199
	v_pk_mul_f32 v[40:41], v[40:41], v[224:225]
	v_pk_mul_f32 v[42:43], v[42:43], v[226:227]
	v_cvt_pk_bf16_f32 v40, v40, v41
	v_cvt_pk_bf16_f32 v41, v42, v43
	v_lshlrev_b32_e32 v228, 16, v200
	v_and_b32_e32 v229, 0xffff0000, v200
	v_lshlrev_b32_e32 v230, 16, v201
	v_and_b32_e32 v231, 0xffff0000, v201
	v_pk_mul_f32 v[44:45], v[44:45], v[228:229]
	v_pk_mul_f32 v[46:47], v[46:47], v[230:231]
	v_cvt_pk_bf16_f32 v42, v44, v45
	v_cvt_pk_bf16_f32 v43, v46, v47
	s_nop 1
	v_permlane32_swap_b32 v40, v42
	v_permlane32_swap_b32 v41, v43
	global_store_dwordx4 v[64:65], v[40:43], off offset:96
	v_lshlrev_b32_e32 v224, 16, v202
	v_and_b32_e32 v225, 0xffff0000, v202
	v_lshlrev_b32_e32 v226, 16, v203
	v_and_b32_e32 v227, 0xffff0000, v203
	v_pk_mul_f32 v[16:17], v[16:17], v[224:225]
	v_pk_mul_f32 v[18:19], v[18:19], v[226:227]
	v_cvt_pk_bf16_f32 v16, v16, v17
	v_cvt_pk_bf16_f32 v17, v18, v19
	v_lshlrev_b32_e32 v228, 16, v204
	v_and_b32_e32 v229, 0xffff0000, v204
	v_lshlrev_b32_e32 v230, 16, v205
	v_and_b32_e32 v231, 0xffff0000, v205
	v_pk_mul_f32 v[20:21], v[20:21], v[228:229]
	v_pk_mul_f32 v[22:23], v[22:23], v[230:231]
	v_cvt_pk_bf16_f32 v18, v20, v21
	v_cvt_pk_bf16_f32 v19, v22, v23
	s_nop 1
	v_permlane32_swap_b32 v16, v18
	v_permlane32_swap_b32 v17, v19
	global_store_dwordx4 v[64:65], v[16:19], off offset:128
	v_lshlrev_b32_e32 v224, 16, v206
	v_and_b32_e32 v225, 0xffff0000, v206
	v_lshlrev_b32_e32 v226, 16, v207
	v_and_b32_e32 v227, 0xffff0000, v207
	v_pk_mul_f32 v[24:25], v[24:25], v[224:225]
	v_pk_mul_f32 v[26:27], v[26:27], v[226:227]
	v_cvt_pk_bf16_f32 v24, v24, v25
	v_cvt_pk_bf16_f32 v25, v26, v27
	v_lshlrev_b32_e32 v228, 16, v208
	v_and_b32_e32 v229, 0xffff0000, v208
	v_lshlrev_b32_e32 v230, 16, v209
	v_and_b32_e32 v231, 0xffff0000, v209
	v_pk_mul_f32 v[28:29], v[28:29], v[228:229]
	v_pk_mul_f32 v[30:31], v[30:31], v[230:231]
	v_cvt_pk_bf16_f32 v26, v28, v29
	v_cvt_pk_bf16_f32 v27, v30, v31
	s_nop 1
	v_permlane32_swap_b32 v24, v26
	v_permlane32_swap_b32 v25, v27
	global_store_dwordx4 v[64:65], v[24:27], off offset:160
	v_lshlrev_b32_e32 v224, 16, v210
	v_and_b32_e32 v225, 0xffff0000, v210
	v_lshlrev_b32_e32 v226, 16, v211
	v_and_b32_e32 v227, 0xffff0000, v211
	v_pk_mul_f32 v[0:1], v[0:1], v[224:225]
	v_pk_mul_f32 v[2:3], v[2:3], v[226:227]
	v_cvt_pk_bf16_f32 v0, v0, v1
	v_cvt_pk_bf16_f32 v1, v2, v3
	v_lshlrev_b32_e32 v228, 16, v212
	v_and_b32_e32 v229, 0xffff0000, v212
	v_lshlrev_b32_e32 v230, 16, v213
	v_and_b32_e32 v231, 0xffff0000, v213
	v_pk_mul_f32 v[4:5], v[4:5], v[228:229]
	v_pk_mul_f32 v[6:7], v[6:7], v[230:231]
	v_cvt_pk_bf16_f32 v2, v4, v5
	v_cvt_pk_bf16_f32 v3, v6, v7
	s_nop 1
	v_permlane32_swap_b32 v0, v2
	v_permlane32_swap_b32 v1, v3
	global_store_dwordx4 v[64:65], v[0:3], off offset:192
	v_lshlrev_b32_e32 v224, 16, v232
	v_and_b32_e32 v225, 0xffff0000, v232
	v_lshlrev_b32_e32 v226, 16, v233
	v_and_b32_e32 v227, 0xffff0000, v233
	v_pk_mul_f32 v[8:9], v[8:9], v[224:225]
	v_pk_mul_f32 v[10:11], v[10:11], v[226:227]
	v_cvt_pk_bf16_f32 v8, v8, v9
	v_cvt_pk_bf16_f32 v9, v10, v11
	v_lshlrev_b32_e32 v228, 16, v234
	v_and_b32_e32 v229, 0xffff0000, v234
	v_lshlrev_b32_e32 v230, 16, v235
	v_and_b32_e32 v231, 0xffff0000, v235
	v_pk_mul_f32 v[12:13], v[12:13], v[228:229]
	v_pk_mul_f32 v[14:15], v[14:15], v[230:231]
	v_cvt_pk_bf16_f32 v10, v12, v13
	v_cvt_pk_bf16_f32 v11, v14, v15
	s_nop 1
	v_permlane32_swap_b32 v8, v10
	v_permlane32_swap_b32 v9, v11
	global_store_dwordx4 v[64:65], v[8:11], off offset:224
	s_waitcnt lgkmcnt(0)
	s_barrier
